# window loop: interior tiles convert straight from the exp registers (no 8-register copy, one branch pair fewer)
# baseline (speedup 1.0000x reference)
.LBB0_677:
	ds_read_b128 v[190:193], v243
	ds_read_b128 v[186:189], v243 offset:2048
	ds_read_b128 v[194:197], v244
	ds_read_b128 v[182:185], v244 offset:2048
	s_cmp_le_i32 s73, s65
	ds_read_b128 v[166:169], v217 offset:4096
	ds_read_b128 v[170:173], v217 offset:5120
	s_waitcnt vmcnt(3) lgkmcnt(5)
	v_mfma_f32_16x16x32_bf16 v[0:3], v[190:193], v[36:39], 0
	s_cselect_b64 s[2:3], -1, 0
	s_add_i32 s42, s73, 31
	ds_read_b128 v[174:177], v217 offset:6144
	ds_read_b128 v[178:181], v217 offset:7168
	s_waitcnt vmcnt(2) lgkmcnt(6)
	v_mfma_f32_16x16x32_bf16 v[4:7], v[186:189], v[36:39], 0
	s_cmp_gt_i32 s42, s41
	s_cselect_b64 s[42:43], -1, 0
	s_or_b64 s[48:49], s[42:43], s[2:3]
	s_waitcnt lgkmcnt(5)
	v_mfma_f32_16x16x32_bf16 v[0:3], v[194:197], v[40:43], v[0:3]
	s_mov_b64 s[42:43], -1
	s_and_b64 vcc, exec, s[48:49]
	v_add_u32_e32 v245, s71, v242
	s_waitcnt lgkmcnt(4)
	v_mfma_f32_16x16x32_bf16 v[4:7], v[182:185], v[40:43], v[4:7]
	s_waitcnt vmcnt(1)
	s_nop 1
	v_exp_f32_e32 v8, v0
	v_exp_f32_e32 v9, v1
	v_exp_f32_e32 v10, v2
	v_exp_f32_e32 v11, v3
	s_waitcnt vmcnt(0)
	v_exp_f32_e32 v12, v4
	v_exp_f32_e32 v13, v5
	v_exp_f32_e32 v14, v6
	v_exp_f32_e32 v15, v7
	s_cbranch_vccz .LBB0_679
	v_add_u32_e32 v7, 0xffffc040, v245
	s_mov_b64 s[42:43], 0
	v_add_u32_e32 v0, 0x1ff, v7
	v_cmp_gt_u32_e32 vcc, s13, v0
	v_add_u32_e32 v2, 0x201, v7
	v_add_u32_e32 v3, 0x202, v7
	v_cndmask_b32_e32 v0, 0, v8, vcc
	v_cmp_lt_u32_e32 vcc, s17, v7
	v_add_u32_e32 v4, 0x20f, v7
	v_add_u32_e32 v5, 0x210, v7
	v_cndmask_b32_e32 v1, 0, v9, vcc
	v_cmp_gt_u32_e32 vcc, s13, v2
	v_add_u32_e32 v6, 0x211, v7
	v_add_u32_e32 v7, 0x212, v7
	v_cndmask_b32_e32 v2, 0, v10, vcc
	v_cmp_gt_u32_e32 vcc, s13, v3
	s_nop 1
	v_cndmask_b32_e32 v3, 0, v11, vcc
	v_cmp_gt_u32_e32 vcc, s13, v4
	s_nop 1
	v_cndmask_b32_e32 v4, 0, v12, vcc
	v_cmp_gt_u32_e32 vcc, s13, v5
	s_nop 1
	v_cndmask_b32_e32 v5, 0, v13, vcc
	v_cmp_gt_u32_e32 vcc, s13, v6
	s_nop 1
	v_cndmask_b32_e32 v6, 0, v14, vcc
	v_cmp_gt_u32_e32 vcc, s13, v7
	s_nop 1
	v_cndmask_b32_e32 v7, 0, v15, vcc
	s_branch .LBB0_681
.LBB0_679:
	v_cvt_pk_bf16_f32 v0, v8, v9
	v_cvt_pk_bf16_f32 v1, v10, v11
	v_cvt_pk_bf16_f32 v2, v12, v13
	v_cvt_pk_bf16_f32 v3, v14, v15
	s_branch .Lwc_11

.Lwc_11:
	v_mfma_f32_16x16x32_bf16 v[4:7], v[186:189], v[44:47], 0
	v_cndmask_b32_e64 v8, 0, 1, s[48:49]
	s_mov_b64 s[50:51], -1
	v_cmp_ne_u32_e64 s[42:43], 1, v8
	s_waitcnt lgkmcnt(3)
	v_mfma_f32_16x16x32_bf16 v[146:149], v[166:169], v[0:3], v[146:149]
	s_andn2_b64 vcc, exec, s[48:49]
	s_waitcnt lgkmcnt(2)
	v_mfma_f32_16x16x32_bf16 v[142:145], v[170:173], v[0:3], v[142:145]
	s_waitcnt lgkmcnt(1)
	v_mfma_f32_16x16x32_bf16 v[138:141], v[174:177], v[0:3], v[138:141]
	s_waitcnt lgkmcnt(0)
	v_mfma_f32_16x16x32_bf16 v[134:137], v[178:181], v[0:3], v[134:137]
	v_mfma_f32_16x16x32_bf16 v[162:165], v[72:75], v[0:3], v[162:165]
	v_mfma_f32_16x16x32_bf16 v[0:3], v[190:193], v[44:47], 0
	v_mfma_f32_16x16x32_bf16 v[0:3], v[194:197], v[48:51], v[0:3]
	v_mfma_f32_16x16x32_bf16 v[4:7], v[182:185], v[48:51], v[4:7]
	s_nop 6
	v_exp_f32_e32 v0, v0
	v_exp_f32_e32 v1, v1
	v_exp_f32_e32 v2, v2
	v_exp_f32_e32 v3, v3
	v_exp_f32_e32 v4, v4
	v_exp_f32_e32 v5, v5
	v_exp_f32_e32 v6, v6
	v_exp_f32_e32 v7, v7
	s_cbranch_vccnz .LBB0_683
	v_add_u32_e32 v15, 0xffffc03c, v245
	s_mov_b64 s[50:51], 0
	v_add_u32_e32 v8, 0x1ff, v15
	v_cmp_gt_u32_e32 vcc, s13, v8
	v_add_u32_e32 v10, 0x201, v15
	v_add_u32_e32 v11, 0x202, v15
	v_cndmask_b32_e32 v8, 0, v0, vcc
	v_cmp_lt_u32_e32 vcc, s17, v15
	v_add_u32_e32 v12, 0x20f, v15
	v_add_u32_e32 v13, 0x210, v15
	v_cndmask_b32_e32 v9, 0, v1, vcc
	v_cmp_gt_u32_e32 vcc, s13, v10
	v_add_u32_e32 v14, 0x211, v15
	v_add_u32_e32 v15, 0x212, v15
	v_cndmask_b32_e32 v10, 0, v2, vcc
	v_cmp_gt_u32_e32 vcc, s13, v11
	s_nop 1
	v_cndmask_b32_e32 v11, 0, v3, vcc
	v_cmp_gt_u32_e32 vcc, s13, v12
	s_nop 1
	v_cndmask_b32_e32 v12, 0, v4, vcc
	v_cmp_gt_u32_e32 vcc, s13, v13
	s_nop 1
	v_cndmask_b32_e32 v13, 0, v5, vcc
	v_cmp_gt_u32_e32 vcc, s13, v14
	s_nop 1
	v_cndmask_b32_e32 v14, 0, v6, vcc
	v_cmp_gt_u32_e32 vcc, s13, v15
	s_nop 1
	v_cndmask_b32_e32 v15, 0, v7, vcc
	s_branch .LBB0_685
.LBB0_683:
	v_cvt_pk_bf16_f32 v0, v0, v1
	v_cvt_pk_bf16_f32 v1, v2, v3
	v_cvt_pk_bf16_f32 v2, v4, v5
	v_cvt_pk_bf16_f32 v3, v6, v7
	s_branch .Lwc_10

.Lwc_10:
	v_mfma_f32_16x16x32_bf16 v[4:7], v[186:189], v[52:55], 0
	s_mov_b64 s[48:49], -1
	s_and_b64 vcc, exec, s[42:43]
	v_mfma_f32_16x16x32_bf16 v[130:133], v[166:169], v[0:3], v[130:133]
	v_mfma_f32_16x16x32_bf16 v[124:127], v[170:173], v[0:3], v[124:127]
	v_mfma_f32_16x16x32_bf16 v[120:123], v[174:177], v[0:3], v[120:123]
	v_mfma_f32_16x16x32_bf16 v[116:119], v[178:181], v[0:3], v[116:119]
	v_mfma_f32_16x16x32_bf16 v[158:161], v[72:75], v[0:3], v[158:161]
	v_mfma_f32_16x16x32_bf16 v[0:3], v[190:193], v[52:55], 0
	v_mfma_f32_16x16x32_bf16 v[0:3], v[194:197], v[56:59], v[0:3]
	v_mfma_f32_16x16x32_bf16 v[4:7], v[182:185], v[56:59], v[4:7]
	s_nop 6
	v_exp_f32_e32 v0, v0
	v_exp_f32_e32 v1, v1
	v_exp_f32_e32 v2, v2
	v_exp_f32_e32 v3, v3
	v_exp_f32_e32 v4, v4
	v_exp_f32_e32 v5, v5
	v_exp_f32_e32 v6, v6
	v_exp_f32_e32 v7, v7
	s_cbranch_vccnz .LBB0_687
	v_add_u32_e32 v15, 0xffffc038, v245
	s_mov_b64 s[48:49], 0
	v_add_u32_e32 v8, 0x1ff, v15
	v_cmp_gt_u32_e32 vcc, s13, v8
	v_add_u32_e32 v10, 0x201, v15
	v_add_u32_e32 v11, 0x202, v15
	v_cndmask_b32_e32 v8, 0, v0, vcc
	v_cmp_lt_u32_e32 vcc, s17, v15
	v_add_u32_e32 v12, 0x20f, v15
	v_add_u32_e32 v13, 0x210, v15
	v_cndmask_b32_e32 v9, 0, v1, vcc
	v_cmp_gt_u32_e32 vcc, s13, v10
	v_add_u32_e32 v14, 0x211, v15
	v_add_u32_e32 v15, 0x212, v15
	v_cndmask_b32_e32 v10, 0, v2, vcc
	v_cmp_gt_u32_e32 vcc, s13, v11
	s_nop 1
	v_cndmask_b32_e32 v11, 0, v3, vcc
	v_cmp_gt_u32_e32 vcc, s13, v12
	s_nop 1
	v_cndmask_b32_e32 v12, 0, v4, vcc
	v_cmp_gt_u32_e32 vcc, s13, v13
	s_nop 1
	v_cndmask_b32_e32 v13, 0, v5, vcc
	v_cmp_gt_u32_e32 vcc, s13, v14
	s_nop 1
	v_cndmask_b32_e32 v14, 0, v6, vcc
	v_cmp_gt_u32_e32 vcc, s13, v15
	s_nop 1
	v_cndmask_b32_e32 v15, 0, v7, vcc

.LBB0_689:
	v_mfma_f32_16x16x32_bf16 v[0:3], v[190:193], v[60:63], 0
	v_cvt_pk_bf16_f32 v234, v8, v9
	v_cvt_pk_bf16_f32 v235, v10, v11
	v_cvt_pk_bf16_f32 v236, v12, v13
	v_mfma_f32_16x16x32_bf16 v[4:7], v[186:189], v[60:63], 0
	v_cvt_pk_bf16_f32 v237, v14, v15
	s_mov_b64 s[48:49], -1
	s_and_b64 vcc, exec, s[42:43]
	v_mfma_f32_16x16x32_bf16 v[0:3], v[194:197], v[64:67], v[0:3]
	v_mfma_f32_16x16x32_bf16 v[4:7], v[182:185], v[64:67], v[4:7]
	v_mfma_f32_16x16x32_bf16 v[96:99], v[166:169], v[234:237], v[96:99]
	s_nop 5
	v_exp_f32_e32 v0, v0
	v_exp_f32_e32 v1, v1
	v_exp_f32_e32 v2, v2
	v_mfma_f32_16x16x32_bf16 v[92:95], v[170:173], v[234:237], v[92:95]
	v_exp_f32_e32 v3, v3
	v_exp_f32_e32 v4, v4
	v_exp_f32_e32 v5, v5
	v_mfma_f32_16x16x32_bf16 v[88:91], v[174:177], v[234:237], v[88:91]
	v_exp_f32_e32 v6, v6
	v_exp_f32_e32 v7, v7
	v_mfma_f32_16x16x32_bf16 v[84:87], v[178:181], v[234:237], v[84:87]
	v_mfma_f32_16x16x32_bf16 v[154:157], v[72:75], v[234:237], v[154:157]
	s_cbranch_vccnz .LBB0_691
	v_add_u32_e32 v15, 0xffffc034, v245
	s_mov_b64 s[48:49], 0
	v_add_u32_e32 v8, 0x1ff, v15
	v_cmp_gt_u32_e32 vcc, s13, v8
	v_add_u32_e32 v10, 0x201, v15
	v_add_u32_e32 v11, 0x202, v15
	v_cndmask_b32_e32 v8, 0, v0, vcc
	v_cmp_lt_u32_e32 vcc, s17, v15
	v_add_u32_e32 v12, 0x20f, v15
	v_add_u32_e32 v13, 0x210, v15
	v_cndmask_b32_e32 v9, 0, v1, vcc
	v_cmp_gt_u32_e32 vcc, s13, v10
	v_add_u32_e32 v14, 0x211, v15
	v_add_u32_e32 v15, 0x212, v15
	v_cndmask_b32_e32 v10, 0, v2, vcc
	v_cmp_gt_u32_e32 vcc, s13, v11
	s_nop 1
	v_cndmask_b32_e32 v11, 0, v3, vcc
	v_cmp_gt_u32_e32 vcc, s13, v12
	s_nop 1
	v_cndmask_b32_e32 v12, 0, v4, vcc
	v_cmp_gt_u32_e32 vcc, s13, v13
	s_nop 1
	v_cndmask_b32_e32 v13, 0, v5, vcc
	v_cmp_gt_u32_e32 vcc, s13, v14
	s_nop 1
	v_cndmask_b32_e32 v14, 0, v6, vcc
	v_cmp_gt_u32_e32 vcc, s13, v15
	s_nop 1
	v_cndmask_b32_e32 v15, 0, v7, vcc
	s_branch .LBB0_693

.Lwc_9:
	s_add_i32 s2, s73, 32
	s_cmp_le_i32 s2, s65
	v_mfma_f32_16x16x32_bf16 v[80:83], v[166:169], v[0:3], v[80:83]
	s_cselect_b64 s[2:3], -1, 0
	s_add_i32 s42, s73, 63
	s_cmp_gt_i32 s42, s41
	v_mfma_f32_16x16x32_bf16 v[76:79], v[170:173], v[0:3], v[76:79]
	s_cselect_b64 s[42:43], -1, 0
	s_or_b64 s[48:49], s[42:43], s[2:3]
	s_mov_b64 s[42:43], -1
	v_mfma_f32_16x16x32_bf16 v[68:71], v[174:177], v[0:3], v[68:71]
	s_and_b64 vcc, exec, s[48:49]
	v_mfma_f32_16x16x32_bf16 v[32:35], v[178:181], v[0:3], v[32:35]
	ds_read_b128 v[182:185], v243 offset:8192
	ds_read_b128 v[186:189], v244 offset:8192
	ds_read_b128 v[194:197], v243 offset:10240
	ds_read_b128 v[190:193], v244 offset:10240
	ds_read_b128 v[170:173], v217 offset:12288
	ds_read_b128 v[174:177], v217 offset:13312
	ds_read_b128 v[178:181], v217 offset:14336
	ds_read_b128 v[166:169], v217 offset:15360
	v_mfma_f32_16x16x32_bf16 v[150:153], v[72:75], v[0:3], v[150:153]
	s_waitcnt lgkmcnt(7)
	v_mfma_f32_16x16x32_bf16 v[0:3], v[182:185], v[36:39], 0
	s_waitcnt lgkmcnt(5)
	v_mfma_f32_16x16x32_bf16 v[4:7], v[194:197], v[36:39], 0
	v_mfma_f32_16x16x32_bf16 v[0:3], v[186:189], v[40:43], v[0:3]
	s_waitcnt lgkmcnt(4)
	v_mfma_f32_16x16x32_bf16 v[4:7], v[190:193], v[40:43], v[4:7]
	s_nop 5
	v_exp_f32_e32 v0, v0
	v_exp_f32_e32 v1, v1
	v_exp_f32_e32 v2, v2
	v_exp_f32_e32 v3, v3
	v_exp_f32_e32 v4, v4
	v_exp_f32_e32 v5, v5
	v_exp_f32_e32 v6, v6
	v_exp_f32_e32 v7, v7
	s_cbranch_vccz .LBB0_695
	v_add_u32_e32 v15, 0xffffc060, v245
	s_mov_b64 s[42:43], 0
	v_add_u32_e32 v8, 0x1ff, v15
	v_cmp_gt_u32_e32 vcc, s13, v8
	v_add_u32_e32 v10, 0x201, v15
	v_add_u32_e32 v11, 0x202, v15
	v_cndmask_b32_e32 v8, 0, v0, vcc
	v_cmp_lt_u32_e32 vcc, s17, v15
	v_add_u32_e32 v12, 0x20f, v15
	v_add_u32_e32 v13, 0x210, v15
	v_cndmask_b32_e32 v9, 0, v1, vcc
	v_cmp_gt_u32_e32 vcc, s13, v10
	v_add_u32_e32 v14, 0x211, v15
	v_add_u32_e32 v15, 0x212, v15
	v_cndmask_b32_e32 v10, 0, v2, vcc
	v_cmp_gt_u32_e32 vcc, s13, v11
	s_nop 1
	v_cndmask_b32_e32 v11, 0, v3, vcc
	v_cmp_gt_u32_e32 vcc, s13, v12
	s_nop 1
	v_cndmask_b32_e32 v12, 0, v4, vcc
	v_cmp_gt_u32_e32 vcc, s13, v13
	s_nop 1
	v_cndmask_b32_e32 v13, 0, v5, vcc
	v_cmp_gt_u32_e32 vcc, s13, v14
	s_nop 1
	v_cndmask_b32_e32 v14, 0, v6, vcc
	v_cmp_gt_u32_e32 vcc, s13, v15
	s_nop 1
	v_cndmask_b32_e32 v15, 0, v7, vcc
	s_branch .LBB0_697

.Lwc_8:
	v_mfma_f32_16x16x32_bf16 v[4:7], v[194:197], v[44:47], 0
	v_cndmask_b32_e64 v8, 0, 1, s[48:49]
	s_mov_b64 s[50:51], -1
	v_cmp_ne_u32_e64 s[42:43], 1, v8
	s_waitcnt lgkmcnt(3)
	v_mfma_f32_16x16x32_bf16 v[146:149], v[170:173], v[0:3], v[146:149]
	s_andn2_b64 vcc, exec, s[48:49]
	s_waitcnt lgkmcnt(2)
	v_mfma_f32_16x16x32_bf16 v[142:145], v[174:177], v[0:3], v[142:145]
	s_waitcnt lgkmcnt(1)
	v_mfma_f32_16x16x32_bf16 v[138:141], v[178:181], v[0:3], v[138:141]
	s_waitcnt lgkmcnt(0)
	v_mfma_f32_16x16x32_bf16 v[134:137], v[166:169], v[0:3], v[134:137]
	v_mfma_f32_16x16x32_bf16 v[162:165], v[72:75], v[0:3], v[162:165]
	v_mfma_f32_16x16x32_bf16 v[0:3], v[182:185], v[44:47], 0
	v_mfma_f32_16x16x32_bf16 v[0:3], v[186:189], v[48:51], v[0:3]
	v_mfma_f32_16x16x32_bf16 v[4:7], v[190:193], v[48:51], v[4:7]
	s_nop 6
	v_exp_f32_e32 v0, v0
	v_exp_f32_e32 v1, v1
	v_exp_f32_e32 v2, v2
	v_exp_f32_e32 v3, v3
	v_exp_f32_e32 v4, v4
	v_exp_f32_e32 v5, v5
	v_exp_f32_e32 v6, v6
	v_exp_f32_e32 v7, v7
	s_cbranch_vccnz .LBB0_699
	v_add_u32_e32 v15, 0xffffc05c, v245
	s_mov_b64 s[50:51], 0
	v_add_u32_e32 v8, 0x1ff, v15
	v_cmp_gt_u32_e32 vcc, s13, v8
	v_add_u32_e32 v10, 0x201, v15
	v_add_u32_e32 v11, 0x202, v15
	v_cndmask_b32_e32 v8, 0, v0, vcc
	v_cmp_lt_u32_e32 vcc, s17, v15
	v_add_u32_e32 v12, 0x20f, v15
	v_add_u32_e32 v13, 0x210, v15
	v_cndmask_b32_e32 v9, 0, v1, vcc
	v_cmp_gt_u32_e32 vcc, s13, v10
	v_add_u32_e32 v14, 0x211, v15
	v_add_u32_e32 v15, 0x212, v15
	v_cndmask_b32_e32 v10, 0, v2, vcc
	v_cmp_gt_u32_e32 vcc, s13, v11
	s_nop 1
	v_cndmask_b32_e32 v11, 0, v3, vcc
	v_cmp_gt_u32_e32 vcc, s13, v12
	s_nop 1
	v_cndmask_b32_e32 v12, 0, v4, vcc
	v_cmp_gt_u32_e32 vcc, s13, v13
	s_nop 1
	v_cndmask_b32_e32 v13, 0, v5, vcc
	v_cmp_gt_u32_e32 vcc, s13, v14
	s_nop 1
	v_cndmask_b32_e32 v14, 0, v6, vcc
	v_cmp_gt_u32_e32 vcc, s13, v15
	s_nop 1
	v_cndmask_b32_e32 v15, 0, v7, vcc
	s_branch .LBB0_701

.Lwc_7:
	v_mfma_f32_16x16x32_bf16 v[4:7], v[194:197], v[52:55], 0
	s_mov_b64 s[48:49], -1
	s_and_b64 vcc, exec, s[42:43]
	v_mfma_f32_16x16x32_bf16 v[130:133], v[170:173], v[0:3], v[130:133]
	v_mfma_f32_16x16x32_bf16 v[124:127], v[174:177], v[0:3], v[124:127]
	v_mfma_f32_16x16x32_bf16 v[120:123], v[178:181], v[0:3], v[120:123]
	v_mfma_f32_16x16x32_bf16 v[116:119], v[166:169], v[0:3], v[116:119]
	v_mfma_f32_16x16x32_bf16 v[158:161], v[72:75], v[0:3], v[158:161]
	v_mfma_f32_16x16x32_bf16 v[0:3], v[182:185], v[52:55], 0
	v_mfma_f32_16x16x32_bf16 v[0:3], v[186:189], v[56:59], v[0:3]
	v_mfma_f32_16x16x32_bf16 v[4:7], v[190:193], v[56:59], v[4:7]
	s_nop 6
	v_exp_f32_e32 v0, v0
	v_exp_f32_e32 v1, v1
	v_exp_f32_e32 v2, v2
	v_exp_f32_e32 v3, v3
	v_exp_f32_e32 v4, v4
	v_exp_f32_e32 v5, v5
	v_exp_f32_e32 v6, v6
	v_exp_f32_e32 v7, v7
	s_cbranch_vccnz .LBB0_703
	v_add_u32_e32 v15, 0xffffc058, v245
	s_mov_b64 s[48:49], 0
	v_add_u32_e32 v8, 0x1ff, v15
	v_cmp_gt_u32_e32 vcc, s13, v8
	v_add_u32_e32 v10, 0x201, v15
	v_add_u32_e32 v11, 0x202, v15
	v_cndmask_b32_e32 v8, 0, v0, vcc
	v_cmp_lt_u32_e32 vcc, s17, v15
	v_add_u32_e32 v12, 0x20f, v15
	v_add_u32_e32 v13, 0x210, v15
	v_cndmask_b32_e32 v9, 0, v1, vcc
	v_cmp_gt_u32_e32 vcc, s13, v10
	v_add_u32_e32 v14, 0x211, v15
	v_add_u32_e32 v15, 0x212, v15
	v_cndmask_b32_e32 v10, 0, v2, vcc
	v_cmp_gt_u32_e32 vcc, s13, v11
	s_nop 1
	v_cndmask_b32_e32 v11, 0, v3, vcc
	v_cmp_gt_u32_e32 vcc, s13, v12
	s_nop 1
	v_cndmask_b32_e32 v12, 0, v4, vcc
	v_cmp_gt_u32_e32 vcc, s13, v13
	s_nop 1
	v_cndmask_b32_e32 v13, 0, v5, vcc
	v_cmp_gt_u32_e32 vcc, s13, v14
	s_nop 1
	v_cndmask_b32_e32 v14, 0, v6, vcc
	v_cmp_gt_u32_e32 vcc, s13, v15
	s_nop 1
	v_cndmask_b32_e32 v15, 0, v7, vcc

.LBB0_705:
	v_mfma_f32_16x16x32_bf16 v[0:3], v[182:185], v[60:63], 0
	v_cvt_pk_bf16_f32 v234, v8, v9
	v_cvt_pk_bf16_f32 v235, v10, v11
	v_cvt_pk_bf16_f32 v236, v12, v13
	v_mfma_f32_16x16x32_bf16 v[4:7], v[194:197], v[60:63], 0
	v_cvt_pk_bf16_f32 v237, v14, v15
	s_mov_b64 s[48:49], -1
	s_and_b64 vcc, exec, s[42:43]
	v_mfma_f32_16x16x32_bf16 v[0:3], v[186:189], v[64:67], v[0:3]
	v_mfma_f32_16x16x32_bf16 v[4:7], v[190:193], v[64:67], v[4:7]
	v_mfma_f32_16x16x32_bf16 v[96:99], v[170:173], v[234:237], v[96:99]
	s_nop 5
	v_exp_f32_e32 v0, v0
	v_exp_f32_e32 v1, v1
	v_exp_f32_e32 v2, v2
	v_mfma_f32_16x16x32_bf16 v[92:95], v[174:177], v[234:237], v[92:95]
	v_exp_f32_e32 v3, v3
	v_exp_f32_e32 v4, v4
	v_exp_f32_e32 v5, v5
	v_mfma_f32_16x16x32_bf16 v[88:91], v[178:181], v[234:237], v[88:91]
	v_exp_f32_e32 v6, v6
	v_exp_f32_e32 v7, v7
	v_mfma_f32_16x16x32_bf16 v[84:87], v[166:169], v[234:237], v[84:87]
	v_mfma_f32_16x16x32_bf16 v[154:157], v[72:75], v[234:237], v[154:157]
	s_cbranch_vccnz .LBB0_707
	v_add_u32_e32 v15, 0xffffc054, v245
	s_mov_b64 s[48:49], 0
	v_add_u32_e32 v8, 0x1ff, v15
	v_cmp_gt_u32_e32 vcc, s13, v8
	v_add_u32_e32 v10, 0x201, v15
	v_add_u32_e32 v11, 0x202, v15
	v_cndmask_b32_e32 v8, 0, v0, vcc
	v_cmp_lt_u32_e32 vcc, s17, v15
	v_add_u32_e32 v12, 0x20f, v15
	v_add_u32_e32 v13, 0x210, v15
	v_cndmask_b32_e32 v9, 0, v1, vcc
	v_cmp_gt_u32_e32 vcc, s13, v10
	v_add_u32_e32 v14, 0x211, v15
	v_add_u32_e32 v15, 0x212, v15
	v_cndmask_b32_e32 v10, 0, v2, vcc
	v_cmp_gt_u32_e32 vcc, s13, v11
	s_nop 1
	v_cndmask_b32_e32 v11, 0, v3, vcc
	v_cmp_gt_u32_e32 vcc, s13, v12
	s_nop 1
	v_cndmask_b32_e32 v12, 0, v4, vcc
	v_cmp_gt_u32_e32 vcc, s13, v13
	s_nop 1
	v_cndmask_b32_e32 v13, 0, v5, vcc
	v_cmp_gt_u32_e32 vcc, s13, v14
	s_nop 1
	v_cndmask_b32_e32 v14, 0, v6, vcc
	v_cmp_gt_u32_e32 vcc, s13, v15
	s_nop 1
	v_cndmask_b32_e32 v15, 0, v7, vcc
	s_branch .LBB0_709

.Lwc_6:
	s_waitcnt lgkmcnt(0)
	s_andn2_b64 vcc, exec, s[46:47]
	s_barrier
	v_mfma_f32_16x16x32_bf16 v[80:83], v[170:173], v[0:3], v[80:83]
	v_mfma_f32_16x16x32_bf16 v[76:79], v[174:177], v[0:3], v[76:79]
	v_mfma_f32_16x16x32_bf16 v[68:71], v[178:181], v[0:3], v[68:71]
	v_mfma_f32_16x16x32_bf16 v[32:35], v[166:169], v[0:3], v[32:35]
	v_mfma_f32_16x16x32_bf16 v[150:153], v[72:75], v[0:3], v[150:153]
	s_cbranch_vccnz .LBB0_747
	s_add_i32 s2, s74, 2
	s_cmp_gt_i32 s2, s29
	s_cbranch_scc1 .LBB0_712
	ds_write_b128 v215, v[16:19]
	ds_write_b128 v215, v[20:23] offset:8192
	ds_write_b128 v216, v[24:27] offset:4096
	ds_write_b128 v216, v[28:31] offset:12288

.LBB0_714:
	ds_read_b128 v[190:193], v243 offset:16384
	ds_read_b128 v[194:197], v244 offset:16384
	ds_read_b128 v[186:189], v243 offset:18432
	ds_read_b128 v[182:185], v244 offset:18432
	s_add_i32 s2, s73, 64
	s_cmp_le_i32 s2, s65
	s_waitcnt lgkmcnt(3)
	v_mfma_f32_16x16x32_bf16 v[0:3], v[190:193], v[36:39], 0
	ds_read_b128 v[166:169], v217 offset:20480
	ds_read_b128 v[170:173], v217 offset:21504
	s_cselect_b64 s[2:3], -1, 0
	s_add_i32 s42, s73, 0x5f
	s_waitcnt lgkmcnt(3)
	v_mfma_f32_16x16x32_bf16 v[4:7], v[186:189], v[36:39], 0
	ds_read_b128 v[174:177], v217 offset:22528
	ds_read_b128 v[178:181], v217 offset:23552
	s_cmp_gt_i32 s42, s41
	s_cselect_b64 s[42:43], -1, 0
	v_mfma_f32_16x16x32_bf16 v[0:3], v[194:197], v[40:43], v[0:3]
	s_or_b64 s[46:47], s[42:43], s[2:3]
	s_mov_b64 s[42:43], -1
	s_and_b64 vcc, exec, s[46:47]
	s_waitcnt lgkmcnt(4)
	v_mfma_f32_16x16x32_bf16 v[4:7], v[182:185], v[40:43], v[4:7]
	s_nop 2
	v_exp_f32_e32 v0, v0
	v_exp_f32_e32 v1, v1
	v_exp_f32_e32 v2, v2
	v_exp_f32_e32 v3, v3
	s_nop 0
	v_exp_f32_e32 v4, v4
	v_exp_f32_e32 v5, v5
	v_exp_f32_e32 v6, v6
	v_exp_f32_e32 v7, v7
	s_cbranch_vccz .LBB0_716
	v_add_u32_e32 v15, 0xffffc080, v245
	s_mov_b64 s[42:43], 0
	v_add_u32_e32 v8, 0x1ff, v15
	v_cmp_gt_u32_e32 vcc, s13, v8
	v_add_u32_e32 v10, 0x201, v15
	v_add_u32_e32 v11, 0x202, v15
	v_cndmask_b32_e32 v8, 0, v0, vcc
	v_cmp_lt_u32_e32 vcc, s17, v15
	v_add_u32_e32 v12, 0x20f, v15
	v_add_u32_e32 v13, 0x210, v15
	v_cndmask_b32_e32 v9, 0, v1, vcc
	v_cmp_gt_u32_e32 vcc, s13, v10
	v_add_u32_e32 v14, 0x211, v15
	v_add_u32_e32 v15, 0x212, v15
	v_cndmask_b32_e32 v10, 0, v2, vcc
	v_cmp_gt_u32_e32 vcc, s13, v11
	s_nop 1
	v_cndmask_b32_e32 v11, 0, v3, vcc
	v_cmp_gt_u32_e32 vcc, s13, v12
	s_nop 1
	v_cndmask_b32_e32 v12, 0, v4, vcc
	v_cmp_gt_u32_e32 vcc, s13, v13
	s_nop 1
	v_cndmask_b32_e32 v13, 0, v5, vcc
	v_cmp_gt_u32_e32 vcc, s13, v14
	s_nop 1
	v_cndmask_b32_e32 v14, 0, v6, vcc
	v_cmp_gt_u32_e32 vcc, s13, v15
	s_nop 1
	v_cndmask_b32_e32 v15, 0, v7, vcc
	s_branch .LBB0_718

.Lwc_5:
	v_mfma_f32_16x16x32_bf16 v[4:7], v[186:189], v[44:47], 0
	v_cndmask_b32_e64 v8, 0, 1, s[46:47]
	s_mov_b64 s[48:49], -1
	v_cmp_ne_u32_e64 s[42:43], 1, v8
	s_waitcnt lgkmcnt(3)
	v_mfma_f32_16x16x32_bf16 v[146:149], v[166:169], v[0:3], v[146:149]
	s_andn2_b64 vcc, exec, s[46:47]
	s_waitcnt lgkmcnt(2)
	v_mfma_f32_16x16x32_bf16 v[142:145], v[170:173], v[0:3], v[142:145]
	s_waitcnt lgkmcnt(1)
	v_mfma_f32_16x16x32_bf16 v[138:141], v[174:177], v[0:3], v[138:141]
	s_waitcnt lgkmcnt(0)
	v_mfma_f32_16x16x32_bf16 v[134:137], v[178:181], v[0:3], v[134:137]
	v_mfma_f32_16x16x32_bf16 v[162:165], v[72:75], v[0:3], v[162:165]
	v_mfma_f32_16x16x32_bf16 v[0:3], v[190:193], v[44:47], 0
	v_mfma_f32_16x16x32_bf16 v[0:3], v[194:197], v[48:51], v[0:3]
	v_mfma_f32_16x16x32_bf16 v[4:7], v[182:185], v[48:51], v[4:7]
	s_nop 6
	v_exp_f32_e32 v0, v0
	v_exp_f32_e32 v1, v1
	v_exp_f32_e32 v2, v2
	v_exp_f32_e32 v3, v3
	v_exp_f32_e32 v4, v4
	v_exp_f32_e32 v5, v5
	v_exp_f32_e32 v6, v6
	v_exp_f32_e32 v7, v7
	s_cbranch_vccnz .LBB0_720
	v_add_u32_e32 v15, 0xffffc07c, v245
	s_mov_b64 s[48:49], 0
	v_add_u32_e32 v8, 0x1ff, v15
	v_cmp_gt_u32_e32 vcc, s13, v8
	v_add_u32_e32 v10, 0x201, v15
	v_add_u32_e32 v11, 0x202, v15
	v_cndmask_b32_e32 v8, 0, v0, vcc
	v_cmp_lt_u32_e32 vcc, s17, v15
	v_add_u32_e32 v12, 0x20f, v15
	v_add_u32_e32 v13, 0x210, v15
	v_cndmask_b32_e32 v9, 0, v1, vcc
	v_cmp_gt_u32_e32 vcc, s13, v10
	v_add_u32_e32 v14, 0x211, v15
	v_add_u32_e32 v15, 0x212, v15
	v_cndmask_b32_e32 v10, 0, v2, vcc
	v_cmp_gt_u32_e32 vcc, s13, v11
	s_nop 1
	v_cndmask_b32_e32 v11, 0, v3, vcc
	v_cmp_gt_u32_e32 vcc, s13, v12
	s_nop 1
	v_cndmask_b32_e32 v12, 0, v4, vcc
	v_cmp_gt_u32_e32 vcc, s13, v13
	s_nop 1
	v_cndmask_b32_e32 v13, 0, v5, vcc
	v_cmp_gt_u32_e32 vcc, s13, v14
	s_nop 1
	v_cndmask_b32_e32 v14, 0, v6, vcc
	v_cmp_gt_u32_e32 vcc, s13, v15
	s_nop 1
	v_cndmask_b32_e32 v15, 0, v7, vcc
	s_branch .LBB0_722

.Lwc_4:
	v_mfma_f32_16x16x32_bf16 v[4:7], v[186:189], v[52:55], 0
	s_mov_b64 s[46:47], -1
	s_and_b64 vcc, exec, s[42:43]
	v_mfma_f32_16x16x32_bf16 v[130:133], v[166:169], v[0:3], v[130:133]
	v_mfma_f32_16x16x32_bf16 v[124:127], v[170:173], v[0:3], v[124:127]
	v_mfma_f32_16x16x32_bf16 v[120:123], v[174:177], v[0:3], v[120:123]
	v_mfma_f32_16x16x32_bf16 v[116:119], v[178:181], v[0:3], v[116:119]
	v_mfma_f32_16x16x32_bf16 v[158:161], v[72:75], v[0:3], v[158:161]
	v_mfma_f32_16x16x32_bf16 v[0:3], v[190:193], v[52:55], 0
	v_mfma_f32_16x16x32_bf16 v[0:3], v[194:197], v[56:59], v[0:3]
	v_mfma_f32_16x16x32_bf16 v[4:7], v[182:185], v[56:59], v[4:7]
	s_nop 6
	v_exp_f32_e32 v0, v0
	v_exp_f32_e32 v1, v1
	v_exp_f32_e32 v2, v2
	v_exp_f32_e32 v3, v3
	v_exp_f32_e32 v4, v4
	v_exp_f32_e32 v5, v5
	v_exp_f32_e32 v6, v6
	v_exp_f32_e32 v7, v7
	s_cbranch_vccnz .LBB0_724
	v_add_u32_e32 v15, 0xffffc078, v245
	s_mov_b64 s[46:47], 0
	v_add_u32_e32 v8, 0x1ff, v15
	v_cmp_gt_u32_e32 vcc, s13, v8
	v_add_u32_e32 v10, 0x201, v15
	v_add_u32_e32 v11, 0x202, v15
	v_cndmask_b32_e32 v8, 0, v0, vcc
	v_cmp_lt_u32_e32 vcc, s17, v15
	v_add_u32_e32 v12, 0x20f, v15
	v_add_u32_e32 v13, 0x210, v15
	v_cndmask_b32_e32 v9, 0, v1, vcc
	v_cmp_gt_u32_e32 vcc, s13, v10
	v_add_u32_e32 v14, 0x211, v15
	v_add_u32_e32 v15, 0x212, v15
	v_cndmask_b32_e32 v10, 0, v2, vcc
	v_cmp_gt_u32_e32 vcc, s13, v11
	s_nop 1
	v_cndmask_b32_e32 v11, 0, v3, vcc
	v_cmp_gt_u32_e32 vcc, s13, v12
	s_nop 1
	v_cndmask_b32_e32 v12, 0, v4, vcc
	v_cmp_gt_u32_e32 vcc, s13, v13
	s_nop 1
	v_cndmask_b32_e32 v13, 0, v5, vcc
	v_cmp_gt_u32_e32 vcc, s13, v14
	s_nop 1
	v_cndmask_b32_e32 v14, 0, v6, vcc
	v_cmp_gt_u32_e32 vcc, s13, v15
	s_nop 1
	v_cndmask_b32_e32 v15, 0, v7, vcc

.LBB0_726:
	v_mfma_f32_16x16x32_bf16 v[0:3], v[190:193], v[60:63], 0
	v_cvt_pk_bf16_f32 v234, v8, v9
	v_cvt_pk_bf16_f32 v235, v10, v11
	v_cvt_pk_bf16_f32 v236, v12, v13
	v_mfma_f32_16x16x32_bf16 v[4:7], v[186:189], v[60:63], 0
	v_cvt_pk_bf16_f32 v237, v14, v15
	s_mov_b64 s[46:47], -1
	s_and_b64 vcc, exec, s[42:43]
	v_mfma_f32_16x16x32_bf16 v[0:3], v[194:197], v[64:67], v[0:3]
	v_mfma_f32_16x16x32_bf16 v[4:7], v[182:185], v[64:67], v[4:7]
	v_mfma_f32_16x16x32_bf16 v[96:99], v[166:169], v[234:237], v[96:99]
	s_nop 5
	v_exp_f32_e32 v0, v0
	v_exp_f32_e32 v1, v1
	v_exp_f32_e32 v2, v2
	v_mfma_f32_16x16x32_bf16 v[92:95], v[170:173], v[234:237], v[92:95]
	v_exp_f32_e32 v3, v3
	v_exp_f32_e32 v4, v4
	v_exp_f32_e32 v5, v5
	v_mfma_f32_16x16x32_bf16 v[88:91], v[174:177], v[234:237], v[88:91]
	v_exp_f32_e32 v6, v6
	v_exp_f32_e32 v7, v7
	v_mfma_f32_16x16x32_bf16 v[84:87], v[178:181], v[234:237], v[84:87]
	v_mfma_f32_16x16x32_bf16 v[154:157], v[72:75], v[234:237], v[154:157]
	s_cbranch_vccnz .LBB0_728
	v_add_u32_e32 v15, 0xffffc074, v245
	s_mov_b64 s[46:47], 0
	v_add_u32_e32 v8, 0x1ff, v15
	v_cmp_gt_u32_e32 vcc, s13, v8
	v_add_u32_e32 v10, 0x201, v15
	v_add_u32_e32 v11, 0x202, v15
	v_cndmask_b32_e32 v8, 0, v0, vcc
	v_cmp_lt_u32_e32 vcc, s17, v15
	v_add_u32_e32 v12, 0x20f, v15
	v_add_u32_e32 v13, 0x210, v15
	v_cndmask_b32_e32 v9, 0, v1, vcc
	v_cmp_gt_u32_e32 vcc, s13, v10
	v_add_u32_e32 v14, 0x211, v15
	v_add_u32_e32 v15, 0x212, v15
	v_cndmask_b32_e32 v10, 0, v2, vcc
	v_cmp_gt_u32_e32 vcc, s13, v11
	s_nop 1
	v_cndmask_b32_e32 v11, 0, v3, vcc
	v_cmp_gt_u32_e32 vcc, s13, v12
	s_nop 1
	v_cndmask_b32_e32 v12, 0, v4, vcc
	v_cmp_gt_u32_e32 vcc, s13, v13
	s_nop 1
	v_cndmask_b32_e32 v13, 0, v5, vcc
	v_cmp_gt_u32_e32 vcc, s13, v14
	s_nop 1
	v_cndmask_b32_e32 v14, 0, v6, vcc
	v_cmp_gt_u32_e32 vcc, s13, v15
	s_nop 1
	v_cndmask_b32_e32 v15, 0, v7, vcc
	s_branch .LBB0_730

.Lwc_3:
	s_add_i32 s2, s73, 0x60
	s_cmp_le_i32 s2, s65
	v_mfma_f32_16x16x32_bf16 v[80:83], v[166:169], v[0:3], v[80:83]
	s_cselect_b64 s[2:3], -1, 0
	s_addk_i32 s73, 0x7f
	s_cmp_gt_i32 s73, s41
	v_mfma_f32_16x16x32_bf16 v[76:79], v[170:173], v[0:3], v[76:79]
	s_cselect_b64 s[42:43], -1, 0
	s_or_b64 s[46:47], s[42:43], s[2:3]
	s_mov_b64 s[42:43], -1
	v_mfma_f32_16x16x32_bf16 v[68:71], v[174:177], v[0:3], v[68:71]
	s_and_b64 vcc, exec, s[46:47]
	v_mfma_f32_16x16x32_bf16 v[32:35], v[178:181], v[0:3], v[32:35]
	ds_read_b128 v[182:185], v243 offset:24576
	ds_read_b128 v[186:189], v244 offset:24576
	ds_read_b128 v[194:197], v243 offset:26624
	ds_read_b128 v[190:193], v244 offset:26624
	ds_read_b128 v[166:169], v217 offset:28672
	ds_read_b128 v[170:173], v217 offset:29696
	ds_read_b128 v[174:177], v217 offset:30720
	ds_read_b128 v[178:181], v217 offset:31744
	v_mfma_f32_16x16x32_bf16 v[150:153], v[72:75], v[0:3], v[150:153]
	s_waitcnt lgkmcnt(7)
	v_mfma_f32_16x16x32_bf16 v[0:3], v[182:185], v[36:39], 0
	s_waitcnt lgkmcnt(5)
	v_mfma_f32_16x16x32_bf16 v[4:7], v[194:197], v[36:39], 0
	v_mfma_f32_16x16x32_bf16 v[0:3], v[186:189], v[40:43], v[0:3]
	s_waitcnt lgkmcnt(4)
	v_mfma_f32_16x16x32_bf16 v[4:7], v[190:193], v[40:43], v[4:7]
	s_nop 5
	v_exp_f32_e32 v0, v0
	v_exp_f32_e32 v1, v1
	v_exp_f32_e32 v2, v2
	v_exp_f32_e32 v3, v3
	v_exp_f32_e32 v4, v4
	v_exp_f32_e32 v5, v5
	v_exp_f32_e32 v6, v6
	v_exp_f32_e32 v7, v7
	s_cbranch_vccz .LBB0_732
	v_add_u32_e32 v15, 0xffffc0a0, v245
	s_mov_b64 s[42:43], 0
	v_add_u32_e32 v8, 0x1ff, v15
	v_cmp_gt_u32_e32 vcc, s13, v8
	v_add_u32_e32 v10, 0x201, v15
	v_add_u32_e32 v11, 0x202, v15
	v_cndmask_b32_e32 v8, 0, v0, vcc
	v_cmp_lt_u32_e32 vcc, s17, v15
	v_add_u32_e32 v12, 0x20f, v15
	v_add_u32_e32 v13, 0x210, v15
	v_cndmask_b32_e32 v9, 0, v1, vcc
	v_cmp_gt_u32_e32 vcc, s13, v10
	v_add_u32_e32 v14, 0x211, v15
	v_add_u32_e32 v15, 0x212, v15
	v_cndmask_b32_e32 v10, 0, v2, vcc
	v_cmp_gt_u32_e32 vcc, s13, v11
	s_nop 1
	v_cndmask_b32_e32 v11, 0, v3, vcc
	v_cmp_gt_u32_e32 vcc, s13, v12
	s_nop 1
	v_cndmask_b32_e32 v12, 0, v4, vcc
	v_cmp_gt_u32_e32 vcc, s13, v13
	s_nop 1
	v_cndmask_b32_e32 v13, 0, v5, vcc
	v_cmp_gt_u32_e32 vcc, s13, v14
	s_nop 1
	v_cndmask_b32_e32 v14, 0, v6, vcc
	v_cmp_gt_u32_e32 vcc, s13, v15
	s_nop 1
	v_cndmask_b32_e32 v15, 0, v7, vcc
	s_branch .LBB0_734

.Lwc_2:
	v_mfma_f32_16x16x32_bf16 v[4:7], v[194:197], v[44:47], 0
	v_cndmask_b32_e64 v8, 0, 1, s[46:47]
	s_mov_b64 s[48:49], -1
	v_cmp_ne_u32_e64 s[42:43], 1, v8
	s_waitcnt lgkmcnt(3)
	v_mfma_f32_16x16x32_bf16 v[146:149], v[166:169], v[0:3], v[146:149]
	s_andn2_b64 vcc, exec, s[46:47]
	s_waitcnt lgkmcnt(2)
	v_mfma_f32_16x16x32_bf16 v[142:145], v[170:173], v[0:3], v[142:145]
	s_waitcnt lgkmcnt(1)
	v_mfma_f32_16x16x32_bf16 v[138:141], v[174:177], v[0:3], v[138:141]
	s_waitcnt lgkmcnt(0)
	v_mfma_f32_16x16x32_bf16 v[134:137], v[178:181], v[0:3], v[134:137]
	v_mfma_f32_16x16x32_bf16 v[162:165], v[72:75], v[0:3], v[162:165]
	v_mfma_f32_16x16x32_bf16 v[0:3], v[182:185], v[44:47], 0
	v_mfma_f32_16x16x32_bf16 v[0:3], v[186:189], v[48:51], v[0:3]
	v_mfma_f32_16x16x32_bf16 v[4:7], v[190:193], v[48:51], v[4:7]
	s_nop 6
	v_exp_f32_e32 v0, v0
	v_exp_f32_e32 v1, v1
	v_exp_f32_e32 v2, v2
	v_exp_f32_e32 v3, v3
	v_exp_f32_e32 v4, v4
	v_exp_f32_e32 v5, v5
	v_exp_f32_e32 v6, v6
	v_exp_f32_e32 v7, v7
	s_cbranch_vccnz .LBB0_736
	v_add_u32_e32 v15, 0xffffc09c, v245
	s_mov_b64 s[48:49], 0
	v_add_u32_e32 v8, 0x1ff, v15
	v_cmp_gt_u32_e32 vcc, s13, v8
	v_add_u32_e32 v10, 0x201, v15
	v_add_u32_e32 v11, 0x202, v15
	v_cndmask_b32_e32 v8, 0, v0, vcc
	v_cmp_lt_u32_e32 vcc, s17, v15
	v_add_u32_e32 v12, 0x20f, v15
	v_add_u32_e32 v13, 0x210, v15
	v_cndmask_b32_e32 v9, 0, v1, vcc
	v_cmp_gt_u32_e32 vcc, s13, v10
	v_add_u32_e32 v14, 0x211, v15
	v_add_u32_e32 v15, 0x212, v15
	v_cndmask_b32_e32 v10, 0, v2, vcc
	v_cmp_gt_u32_e32 vcc, s13, v11
	s_nop 1
	v_cndmask_b32_e32 v11, 0, v3, vcc
	v_cmp_gt_u32_e32 vcc, s13, v12
	s_nop 1
	v_cndmask_b32_e32 v12, 0, v4, vcc
	v_cmp_gt_u32_e32 vcc, s13, v13
	s_nop 1
	v_cndmask_b32_e32 v13, 0, v5, vcc
	v_cmp_gt_u32_e32 vcc, s13, v14
	s_nop 1
	v_cndmask_b32_e32 v14, 0, v6, vcc
	v_cmp_gt_u32_e32 vcc, s13, v15
	s_nop 1
	v_cndmask_b32_e32 v15, 0, v7, vcc
	s_branch .LBB0_738

.Lwc_1:
	v_mfma_f32_16x16x32_bf16 v[4:7], v[194:197], v[52:55], 0
	s_mov_b64 s[46:47], -1
	s_and_b64 vcc, exec, s[42:43]
	v_mfma_f32_16x16x32_bf16 v[130:133], v[166:169], v[0:3], v[130:133]
	v_mfma_f32_16x16x32_bf16 v[124:127], v[170:173], v[0:3], v[124:127]
	v_mfma_f32_16x16x32_bf16 v[120:123], v[174:177], v[0:3], v[120:123]
	v_mfma_f32_16x16x32_bf16 v[116:119], v[178:181], v[0:3], v[116:119]
	v_mfma_f32_16x16x32_bf16 v[158:161], v[72:75], v[0:3], v[158:161]
	v_mfma_f32_16x16x32_bf16 v[0:3], v[182:185], v[52:55], 0
	v_mfma_f32_16x16x32_bf16 v[0:3], v[186:189], v[56:59], v[0:3]
	v_mfma_f32_16x16x32_bf16 v[4:7], v[190:193], v[56:59], v[4:7]
	s_nop 6
	v_exp_f32_e32 v0, v0
	v_exp_f32_e32 v1, v1
	v_exp_f32_e32 v2, v2
	v_exp_f32_e32 v3, v3
	v_exp_f32_e32 v4, v4
	v_exp_f32_e32 v5, v5
	v_exp_f32_e32 v6, v6
	v_exp_f32_e32 v7, v7
	s_cbranch_vccnz .LBB0_740
	v_add_u32_e32 v15, 0xffffc098, v245
	s_mov_b64 s[46:47], 0
	v_add_u32_e32 v8, 0x1ff, v15
	v_cmp_gt_u32_e32 vcc, s13, v8
	v_add_u32_e32 v10, 0x201, v15
	v_add_u32_e32 v11, 0x202, v15
	v_cndmask_b32_e32 v8, 0, v0, vcc
	v_cmp_lt_u32_e32 vcc, s17, v15
	v_add_u32_e32 v12, 0x20f, v15
	v_add_u32_e32 v13, 0x210, v15
	v_cndmask_b32_e32 v9, 0, v1, vcc
	v_cmp_gt_u32_e32 vcc, s13, v10
	v_add_u32_e32 v14, 0x211, v15
	v_add_u32_e32 v15, 0x212, v15
	v_cndmask_b32_e32 v10, 0, v2, vcc
	v_cmp_gt_u32_e32 vcc, s13, v11
	s_nop 1
	v_cndmask_b32_e32 v11, 0, v3, vcc
	v_cmp_gt_u32_e32 vcc, s13, v12
	s_nop 1
	v_cndmask_b32_e32 v12, 0, v4, vcc
	v_cmp_gt_u32_e32 vcc, s13, v13
	s_nop 1
	v_cndmask_b32_e32 v13, 0, v5, vcc
	v_cmp_gt_u32_e32 vcc, s13, v14
	s_nop 1
	v_cndmask_b32_e32 v14, 0, v6, vcc
	v_cmp_gt_u32_e32 vcc, s13, v15
	s_nop 1
	v_cndmask_b32_e32 v15, 0, v7, vcc

.LBB0_742:
	v_mfma_f32_16x16x32_bf16 v[0:3], v[182:185], v[60:63], 0
	v_cvt_pk_bf16_f32 v234, v8, v9
	v_cvt_pk_bf16_f32 v235, v10, v11
	v_cvt_pk_bf16_f32 v236, v12, v13
	v_mfma_f32_16x16x32_bf16 v[4:7], v[194:197], v[60:63], 0
	v_cvt_pk_bf16_f32 v237, v14, v15
	s_mov_b64 s[46:47], -1
	s_and_b64 vcc, exec, s[42:43]
	v_mfma_f32_16x16x32_bf16 v[0:3], v[186:189], v[64:67], v[0:3]
	v_mfma_f32_16x16x32_bf16 v[4:7], v[190:193], v[64:67], v[4:7]
	v_mfma_f32_16x16x32_bf16 v[96:99], v[166:169], v[234:237], v[96:99]
	s_nop 5
	v_exp_f32_e32 v0, v0
	v_exp_f32_e32 v1, v1
	v_exp_f32_e32 v2, v2
	v_mfma_f32_16x16x32_bf16 v[92:95], v[170:173], v[234:237], v[92:95]
	v_exp_f32_e32 v3, v3
	v_exp_f32_e32 v4, v4
	v_exp_f32_e32 v5, v5
	v_mfma_f32_16x16x32_bf16 v[88:91], v[174:177], v[234:237], v[88:91]
	v_exp_f32_e32 v6, v6
	v_exp_f32_e32 v7, v7
	v_mfma_f32_16x16x32_bf16 v[84:87], v[178:181], v[234:237], v[84:87]
	v_mfma_f32_16x16x32_bf16 v[154:157], v[72:75], v[234:237], v[154:157]
	s_cbranch_vccnz .LBB0_744
	v_add_u32_e32 v15, 0xffffc094, v245
	s_mov_b64 s[46:47], 0
	v_add_u32_e32 v8, 0x1ff, v15
	v_cmp_gt_u32_e32 vcc, s13, v8
	v_add_u32_e32 v10, 0x201, v15
	v_add_u32_e32 v11, 0x202, v15
	v_cndmask_b32_e32 v8, 0, v0, vcc
	v_cmp_lt_u32_e32 vcc, s17, v15
	v_add_u32_e32 v12, 0x20f, v15
	v_add_u32_e32 v13, 0x210, v15
	v_cndmask_b32_e32 v9, 0, v1, vcc
	v_cmp_gt_u32_e32 vcc, s13, v10
	v_add_u32_e32 v14, 0x211, v15
	v_add_u32_e32 v15, 0x212, v15
	v_cndmask_b32_e32 v10, 0, v2, vcc
	v_cmp_gt_u32_e32 vcc, s13, v11
	s_nop 1
	v_cndmask_b32_e32 v11, 0, v3, vcc
	v_cmp_gt_u32_e32 vcc, s13, v12
	s_nop 1
	v_cndmask_b32_e32 v12, 0, v4, vcc
	v_cmp_gt_u32_e32 vcc, s13, v13
	s_nop 1
	v_cndmask_b32_e32 v13, 0, v5, vcc
	v_cmp_gt_u32_e32 vcc, s13, v14
	s_nop 1
	v_cndmask_b32_e32 v14, 0, v6, vcc
	v_cmp_gt_u32_e32 vcc, s13, v15
	s_nop 1
	v_cndmask_b32_e32 v15, 0, v7, vcc
	s_branch .LBB0_746

.Lwc_0:
	s_waitcnt lgkmcnt(0)
	s_barrier
	s_nop 0
	v_mfma_f32_16x16x32_bf16 v[80:83], v[166:169], v[0:3], v[80:83]
	v_mfma_f32_16x16x32_bf16 v[76:79], v[170:173], v[0:3], v[76:79]
	v_mfma_f32_16x16x32_bf16 v[68:71], v[174:177], v[0:3], v[68:71]
	v_mfma_f32_16x16x32_bf16 v[32:35], v[178:181], v[0:3], v[32:35]
	v_mfma_f32_16x16x32_bf16 v[150:153], v[72:75], v[0:3], v[150:153]
